# baseline (speedup 1.0000x reference)
; #define GAS __attribute__((address_space(1)))
; __device__ __forceinline__ float sigmoidf_(float v) { return __builtin_amdgcn_rcpf(1.f + __builtin_amdgcn_exp2f(-LOG2E * v)); }
; __device__ __forceinline__ void phase_inproj() {
;     ...
;       if (pn < 12) { const int reg = pn >> 1; ld = AW; coff = (pn & 1) * 256;
;         dst = (GAS unsigned short*)(ws + OFF_RA + (reg == 2 ? RA_VF : reg == 3 ? RA_QS : reg == 4 ? RA_KS : RA_VS)); }
;       else if (pn < 16) { ld = DM; coff = (pn - 12) * 256; dst = (GAS unsigned short*)(ws + OFF_SGF); sg = true; }
;       else { ld = DM; coff = (pn - 16) * 256; dst = (GAS unsigned short*)(ws + OFF_SGS); sg = true; }
;     ...
;       if (sg) { INPROJ_STORE(sigmoidf_(v)) } else { INPROJ_STORE(v) }
.LBB0_368:
	v_ashrrev_i32_e32 v218, 2, v170
	v_and_b32_e32 v218, 0xffffffc0, v218
	v_lshrrev_b32_e32 v174, 2, v170
	v_and_b32_e32 v175, 12, v174
	v_or_b32_e32 v176, v218, v175
	v_and_b32_e32 v174, 48, v174
	v_and_b32_e32 v177, 15, v170
	v_lshl_add_u32 v174, v174, 1, v177
	v_mul_lo_u32 v210, v176, s28
	v_add_lshl_u32 v210, v210, v174, 1
	s_lshl_b32 s29, s28, 1
	v_add_u32_e32 v211, s29, v210
	v_add_u32_e32 v212, s29, v211
	v_add_u32_e32 v213, s29, v212
	v_lshl_add_u32 v218, v176, 2, s5
	ds_read_b128 v[178:181], v218
	ds_read_b128 v[182:185], v218 offset:64
	ds_read_b128 v[186:189], v218 offset:128
	ds_read_b128 v[190:193], v218 offset:192
	ds_read_b128 v[194:197], v218 offset:512
	ds_read_b128 v[198:201], v218 offset:576
	ds_read_b128 v[202:205], v218 offset:640
	ds_read_b128 v[206:209], v218 offset:704
	s_lshl_b32 s30, s20, 1
	s_add_u32 s30, s36, s30
	s_addc_u32 s31, s37, 0
	s_mul_i32 s20, s4, s29
	s_add_u32 s30, s30, s20
	s_addc_u32 s31, s31, 0
	s_lshl_b32 s4, s29, 4
	s_mul_i32 s5, s29, 0x50
	v_mov_b32_e32 v214, 0xbfb8aa3b
	v_mov_b32_e32 v215, 0xbfb8aa3b
	v_mov_b32_e32 v216, 1.0
	v_mov_b32_e32 v217, 1.0
	s_waitcnt lgkmcnt(0)
	s_and_b64 vcc, exec, s[34:35]
	s_cbranch_vccz .Lip_gate
	v_pk_mul_f32 v[114:115], v[114:115], v[178:179]
	v_pk_mul_f32 v[116:117], v[116:117], v[180:181]
	v_cvt_pk_bf16_f32 v114, v114, v115
	v_cvt_pk_bf16_f32 v115, v116, v117
	global_store_short v210, v114, s[30:31]
	global_store_short_d16_hi v211, v114, s[30:31]
	global_store_short v212, v115, s[30:31]
	global_store_short_d16_hi v213, v115, s[30:31]
	v_pk_mul_f32 v[118:119], v[118:119], v[178:179]
	v_pk_mul_f32 v[120:121], v[120:121], v[180:181]
	v_cvt_pk_bf16_f32 v118, v118, v119
	v_cvt_pk_bf16_f32 v119, v120, v121
	global_store_short v210, v118, s[30:31] offset:32
	global_store_short_d16_hi v211, v118, s[30:31] offset:32
	global_store_short v212, v119, s[30:31] offset:32
	global_store_short_d16_hi v213, v119, s[30:31] offset:32
	v_pk_mul_f32 v[122:123], v[122:123], v[178:179]
	v_pk_mul_f32 v[124:125], v[124:125], v[180:181]
	v_cvt_pk_bf16_f32 v122, v122, v123
	v_cvt_pk_bf16_f32 v123, v124, v125
	global_store_short v210, v122, s[30:31] offset:256
	global_store_short_d16_hi v211, v122, s[30:31] offset:256
	global_store_short v212, v123, s[30:31] offset:256
	global_store_short_d16_hi v213, v123, s[30:31] offset:256
	v_pk_mul_f32 v[126:127], v[126:127], v[178:179]
	v_pk_mul_f32 v[128:129], v[128:129], v[180:181]
	v_cvt_pk_bf16_f32 v126, v126, v127
	v_cvt_pk_bf16_f32 v127, v128, v129
	global_store_short v210, v126, s[30:31] offset:288
	global_store_short_d16_hi v211, v126, s[30:31] offset:288
	global_store_short v212, v127, s[30:31] offset:288
	global_store_short_d16_hi v213, v127, s[30:31] offset:288
	s_add_u32 s30, s30, s4
	s_addc_u32 s31, s31, 0
	v_pk_mul_f32 v[102:103], v[102:103], v[182:183]
	v_pk_mul_f32 v[104:105], v[104:105], v[184:185]
	v_cvt_pk_bf16_f32 v102, v102, v103
	v_cvt_pk_bf16_f32 v103, v104, v105
	global_store_short v210, v102, s[30:31]
	global_store_short_d16_hi v211, v102, s[30:31]
	global_store_short v212, v103, s[30:31]
	global_store_short_d16_hi v213, v103, s[30:31]
	v_pk_mul_f32 v[98:99], v[98:99], v[182:183]
	v_pk_mul_f32 v[100:101], v[100:101], v[184:185]
	v_cvt_pk_bf16_f32 v98, v98, v99
	v_cvt_pk_bf16_f32 v99, v100, v101
	global_store_short v210, v98, s[30:31] offset:32
	global_store_short_d16_hi v211, v98, s[30:31] offset:32
	global_store_short v212, v99, s[30:31] offset:32
	global_store_short_d16_hi v213, v99, s[30:31] offset:32
	v_pk_mul_f32 v[106:107], v[106:107], v[182:183]
	v_pk_mul_f32 v[108:109], v[108:109], v[184:185]
	v_cvt_pk_bf16_f32 v106, v106, v107
	v_cvt_pk_bf16_f32 v107, v108, v109
	global_store_short v210, v106, s[30:31] offset:256
	global_store_short_d16_hi v211, v106, s[30:31] offset:256
	global_store_short v212, v107, s[30:31] offset:256
	global_store_short_d16_hi v213, v107, s[30:31] offset:256
	v_pk_mul_f32 v[110:111], v[110:111], v[182:183]
	v_pk_mul_f32 v[112:113], v[112:113], v[184:185]
	v_cvt_pk_bf16_f32 v110, v110, v111
	v_cvt_pk_bf16_f32 v111, v112, v113
	global_store_short v210, v110, s[30:31] offset:288
	global_store_short_d16_hi v211, v110, s[30:31] offset:288
	global_store_short v212, v111, s[30:31] offset:288
	global_store_short_d16_hi v213, v111, s[30:31] offset:288
	s_add_u32 s30, s30, s4
	s_addc_u32 s31, s31, 0
	v_pk_mul_f32 v[82:83], v[82:83], v[186:187]
	v_pk_mul_f32 v[84:85], v[84:85], v[188:189]
	v_cvt_pk_bf16_f32 v82, v82, v83
	v_cvt_pk_bf16_f32 v83, v84, v85
	global_store_short v210, v82, s[30:31]
	global_store_short_d16_hi v211, v82, s[30:31]
	global_store_short v212, v83, s[30:31]
	global_store_short_d16_hi v213, v83, s[30:31]
	v_pk_mul_f32 v[86:87], v[86:87], v[186:187]
	v_pk_mul_f32 v[88:89], v[88:89], v[188:189]
	v_cvt_pk_bf16_f32 v86, v86, v87
	v_cvt_pk_bf16_f32 v87, v88, v89
	global_store_short v210, v86, s[30:31] offset:32
	global_store_short_d16_hi v211, v86, s[30:31] offset:32
	global_store_short v212, v87, s[30:31] offset:32
	global_store_short_d16_hi v213, v87, s[30:31] offset:32
	v_pk_mul_f32 v[90:91], v[90:91], v[186:187]
	v_pk_mul_f32 v[92:93], v[92:93], v[188:189]
	v_cvt_pk_bf16_f32 v90, v90, v91
	v_cvt_pk_bf16_f32 v91, v92, v93
	global_store_short v210, v90, s[30:31] offset:256
	global_store_short_d16_hi v211, v90, s[30:31] offset:256
	global_store_short v212, v91, s[30:31] offset:256
	global_store_short_d16_hi v213, v91, s[30:31] offset:256
	v_pk_mul_f32 v[94:95], v[94:95], v[186:187]
	v_pk_mul_f32 v[96:97], v[96:97], v[188:189]
	v_cvt_pk_bf16_f32 v94, v94, v95
	v_cvt_pk_bf16_f32 v95, v96, v97
	global_store_short v210, v94, s[30:31] offset:288
	global_store_short_d16_hi v211, v94, s[30:31] offset:288
	global_store_short v212, v95, s[30:31] offset:288
	global_store_short_d16_hi v213, v95, s[30:31] offset:288
	s_add_u32 s30, s30, s4
	s_addc_u32 s31, s31, 0
	v_pk_mul_f32 v[70:71], v[70:71], v[190:191]
	v_pk_mul_f32 v[72:73], v[72:73], v[192:193]
	v_cvt_pk_bf16_f32 v70, v70, v71
	v_cvt_pk_bf16_f32 v71, v72, v73
	global_store_short v210, v70, s[30:31]
	global_store_short_d16_hi v211, v70, s[30:31]
	global_store_short v212, v71, s[30:31]
	global_store_short_d16_hi v213, v71, s[30:31]
	v_pk_mul_f32 v[66:67], v[66:67], v[190:191]
	v_pk_mul_f32 v[68:69], v[68:69], v[192:193]
	v_cvt_pk_bf16_f32 v66, v66, v67
	v_cvt_pk_bf16_f32 v67, v68, v69
	global_store_short v210, v66, s[30:31] offset:32
	global_store_short_d16_hi v211, v66, s[30:31] offset:32
	global_store_short v212, v67, s[30:31] offset:32
	global_store_short_d16_hi v213, v67, s[30:31] offset:32
	v_pk_mul_f32 v[74:75], v[74:75], v[190:191]
	v_pk_mul_f32 v[76:77], v[76:77], v[192:193]
	v_cvt_pk_bf16_f32 v74, v74, v75
	v_cvt_pk_bf16_f32 v75, v76, v77
	global_store_short v210, v74, s[30:31] offset:256
	global_store_short_d16_hi v211, v74, s[30:31] offset:256
	global_store_short v212, v75, s[30:31] offset:256
	global_store_short_d16_hi v213, v75, s[30:31] offset:256
	v_pk_mul_f32 v[78:79], v[78:79], v[190:191]
	v_pk_mul_f32 v[80:81], v[80:81], v[192:193]
	v_cvt_pk_bf16_f32 v78, v78, v79
	v_cvt_pk_bf16_f32 v79, v80, v81
	global_store_short v210, v78, s[30:31] offset:288
	global_store_short_d16_hi v211, v78, s[30:31] offset:288
	global_store_short v212, v79, s[30:31] offset:288
	global_store_short_d16_hi v213, v79, s[30:31] offset:288
	s_add_u32 s30, s30, s5
	s_addc_u32 s31, s31, 0
	v_pk_mul_f32 v[50:51], v[50:51], v[194:195]
	v_pk_mul_f32 v[52:53], v[52:53], v[196:197]
	v_cvt_pk_bf16_f32 v50, v50, v51
	v_cvt_pk_bf16_f32 v51, v52, v53
	global_store_short v210, v50, s[30:31]
	global_store_short_d16_hi v211, v50, s[30:31]
	global_store_short v212, v51, s[30:31]
	global_store_short_d16_hi v213, v51, s[30:31]
	v_pk_mul_f32 v[54:55], v[54:55], v[194:195]
	v_pk_mul_f32 v[56:57], v[56:57], v[196:197]
	v_cvt_pk_bf16_f32 v54, v54, v55
	v_cvt_pk_bf16_f32 v55, v56, v57
	global_store_short v210, v54, s[30:31] offset:32
	global_store_short_d16_hi v211, v54, s[30:31] offset:32
	global_store_short v212, v55, s[30:31] offset:32
	global_store_short_d16_hi v213, v55, s[30:31] offset:32
	v_pk_mul_f32 v[58:59], v[58:59], v[194:195]
	v_pk_mul_f32 v[60:61], v[60:61], v[196:197]
	v_cvt_pk_bf16_f32 v58, v58, v59
	v_cvt_pk_bf16_f32 v59, v60, v61
	global_store_short v210, v58, s[30:31] offset:256
	global_store_short_d16_hi v211, v58, s[30:31] offset:256
	global_store_short v212, v59, s[30:31] offset:256
	global_store_short_d16_hi v213, v59, s[30:31] offset:256
	v_pk_mul_f32 v[62:63], v[62:63], v[194:195]
	v_pk_mul_f32 v[64:65], v[64:65], v[196:197]
	v_cvt_pk_bf16_f32 v62, v62, v63
	v_cvt_pk_bf16_f32 v63, v64, v65
	global_store_short v210, v62, s[30:31] offset:288
	global_store_short_d16_hi v211, v62, s[30:31] offset:288
	global_store_short v212, v63, s[30:31] offset:288
	global_store_short_d16_hi v213, v63, s[30:31] offset:288
	s_add_u32 s30, s30, s4
	s_addc_u32 s31, s31, 0
	v_pk_mul_f32 v[38:39], v[38:39], v[198:199]
	v_pk_mul_f32 v[40:41], v[40:41], v[200:201]
	v_cvt_pk_bf16_f32 v38, v38, v39
	v_cvt_pk_bf16_f32 v39, v40, v41
	global_store_short v210, v38, s[30:31]
	global_store_short_d16_hi v211, v38, s[30:31]
	global_store_short v212, v39, s[30:31]
	global_store_short_d16_hi v213, v39, s[30:31]
	v_pk_mul_f32 v[34:35], v[34:35], v[198:199]
	v_pk_mul_f32 v[36:37], v[36:37], v[200:201]
	v_cvt_pk_bf16_f32 v34, v34, v35
	v_cvt_pk_bf16_f32 v35, v36, v37
	global_store_short v210, v34, s[30:31] offset:32
	global_store_short_d16_hi v211, v34, s[30:31] offset:32
	global_store_short v212, v35, s[30:31] offset:32
	global_store_short_d16_hi v213, v35, s[30:31] offset:32
	v_pk_mul_f32 v[42:43], v[42:43], v[198:199]
	v_pk_mul_f32 v[44:45], v[44:45], v[200:201]
	v_cvt_pk_bf16_f32 v42, v42, v43
	v_cvt_pk_bf16_f32 v43, v44, v45
	global_store_short v210, v42, s[30:31] offset:256
	global_store_short_d16_hi v211, v42, s[30:31] offset:256
	global_store_short v212, v43, s[30:31] offset:256
	global_store_short_d16_hi v213, v43, s[30:31] offset:256
	v_pk_mul_f32 v[46:47], v[46:47], v[198:199]
	v_pk_mul_f32 v[48:49], v[48:49], v[200:201]
	v_cvt_pk_bf16_f32 v46, v46, v47
	v_cvt_pk_bf16_f32 v47, v48, v49
	global_store_short v210, v46, s[30:31] offset:288
	global_store_short_d16_hi v211, v46, s[30:31] offset:288
	global_store_short v212, v47, s[30:31] offset:288
	global_store_short_d16_hi v213, v47, s[30:31] offset:288
	s_add_u32 s30, s30, s4
	s_addc_u32 s31, s31, 0
	v_pk_mul_f32 v[18:19], v[18:19], v[202:203]
	v_pk_mul_f32 v[20:21], v[20:21], v[204:205]
	v_cvt_pk_bf16_f32 v18, v18, v19
	v_cvt_pk_bf16_f32 v19, v20, v21
	global_store_short v210, v18, s[30:31]
	global_store_short_d16_hi v211, v18, s[30:31]
	global_store_short v212, v19, s[30:31]
	global_store_short_d16_hi v213, v19, s[30:31]
	v_pk_mul_f32 v[22:23], v[22:23], v[202:203]
	v_pk_mul_f32 v[24:25], v[24:25], v[204:205]
	v_cvt_pk_bf16_f32 v22, v22, v23
	v_cvt_pk_bf16_f32 v23, v24, v25
	global_store_short v210, v22, s[30:31] offset:32
	global_store_short_d16_hi v211, v22, s[30:31] offset:32
	global_store_short v212, v23, s[30:31] offset:32
	global_store_short_d16_hi v213, v23, s[30:31] offset:32
	v_pk_mul_f32 v[26:27], v[26:27], v[202:203]
	v_pk_mul_f32 v[28:29], v[28:29], v[204:205]
	v_cvt_pk_bf16_f32 v26, v26, v27
	v_cvt_pk_bf16_f32 v27, v28, v29
	global_store_short v210, v26, s[30:31] offset:256
	global_store_short_d16_hi v211, v26, s[30:31] offset:256
	global_store_short v212, v27, s[30:31] offset:256
; __device__ __forceinline__ float sigmoidf_(float v) { return __builtin_amdgcn_rcpf(1.f + __builtin_amdgcn_exp2f(-LOG2E * v)); }
; __device__ __forceinline__ void phase_inproj() {
;     ...
;       if (sg) { INPROJ_STORE(sigmoidf_(v)) } else { INPROJ_STORE(v) }
	global_store_short_d16_hi v213, v27, s[30:31] offset:256
	v_pk_mul_f32 v[30:31], v[30:31], v[202:203]
	v_pk_mul_f32 v[32:33], v[32:33], v[204:205]
	v_cvt_pk_bf16_f32 v30, v30, v31
	v_cvt_pk_bf16_f32 v31, v32, v33
	global_store_short v210, v30, s[30:31] offset:288
	global_store_short_d16_hi v211, v30, s[30:31] offset:288
	global_store_short v212, v31, s[30:31] offset:288
	global_store_short_d16_hi v213, v31, s[30:31] offset:288
	s_add_u32 s30, s30, s4
	s_addc_u32 s31, s31, 0
	v_pk_mul_f32 v[6:7], v[6:7], v[206:207]
	v_pk_mul_f32 v[8:9], v[8:9], v[208:209]
	v_cvt_pk_bf16_f32 v6, v6, v7
	v_cvt_pk_bf16_f32 v7, v8, v9
	global_store_short v210, v6, s[30:31]
	global_store_short_d16_hi v211, v6, s[30:31]
	global_store_short v212, v7, s[30:31]
	global_store_short_d16_hi v213, v7, s[30:31]
	v_pk_mul_f32 v[2:3], v[2:3], v[206:207]
	v_pk_mul_f32 v[4:5], v[4:5], v[208:209]
	v_cvt_pk_bf16_f32 v2, v2, v3
	v_cvt_pk_bf16_f32 v3, v4, v5
	global_store_short v210, v2, s[30:31] offset:32
	global_store_short_d16_hi v211, v2, s[30:31] offset:32
	global_store_short v212, v3, s[30:31] offset:32
	global_store_short_d16_hi v213, v3, s[30:31] offset:32
	v_pk_mul_f32 v[10:11], v[10:11], v[206:207]
	v_pk_mul_f32 v[12:13], v[12:13], v[208:209]
	v_cvt_pk_bf16_f32 v10, v10, v11
	v_cvt_pk_bf16_f32 v11, v12, v13
	global_store_short v210, v10, s[30:31] offset:256
	global_store_short_d16_hi v211, v10, s[30:31] offset:256
	global_store_short v212, v11, s[30:31] offset:256
	global_store_short_d16_hi v213, v11, s[30:31] offset:256
	v_pk_mul_f32 v[14:15], v[14:15], v[206:207]
	v_pk_mul_f32 v[16:17], v[16:17], v[208:209]
	v_cvt_pk_bf16_f32 v14, v14, v15
	v_cvt_pk_bf16_f32 v15, v16, v17
	global_store_short v210, v14, s[30:31] offset:288
	global_store_short_d16_hi v211, v14, s[30:31] offset:288
	global_store_short v212, v15, s[30:31] offset:288
	global_store_short_d16_hi v213, v15, s[30:31] offset:288
	s_branch .LBB0_372
.Lip_gate:
	v_pk_mul_f32 v[114:115], v[114:115], v[178:179]
	v_pk_mul_f32 v[116:117], v[116:117], v[180:181]
	v_pk_mul_f32 v[174:175], v[214:215], v[114:115]
	v_pk_mul_f32 v[176:177], v[214:215], v[116:117]
	v_exp_f32_e32 v174, v174
	v_exp_f32_e32 v175, v175
	v_exp_f32_e32 v176, v176
	v_exp_f32_e32 v177, v177
	v_pk_add_f32 v[174:175], v[216:217], v[174:175]
	v_pk_add_f32 v[176:177], v[216:217], v[176:177]
	v_rcp_f32_e32 v174, v174
	v_rcp_f32_e32 v175, v175
	v_rcp_f32_e32 v176, v176
	v_rcp_f32_e32 v177, v177
	v_cvt_pk_bf16_f32 v114, v174, v175
	v_cvt_pk_bf16_f32 v115, v176, v177
	global_store_short v210, v114, s[30:31]
	global_store_short_d16_hi v211, v114, s[30:31]
	global_store_short v212, v115, s[30:31]
	global_store_short_d16_hi v213, v115, s[30:31]
	v_pk_mul_f32 v[118:119], v[118:119], v[178:179]
	v_pk_mul_f32 v[120:121], v[120:121], v[180:181]
	v_pk_mul_f32 v[174:175], v[214:215], v[118:119]
	v_pk_mul_f32 v[176:177], v[214:215], v[120:121]
	v_exp_f32_e32 v174, v174
	v_exp_f32_e32 v175, v175
	v_exp_f32_e32 v176, v176
	v_exp_f32_e32 v177, v177
	v_pk_add_f32 v[174:175], v[216:217], v[174:175]
	v_pk_add_f32 v[176:177], v[216:217], v[176:177]
	v_rcp_f32_e32 v174, v174
	v_rcp_f32_e32 v175, v175
	v_rcp_f32_e32 v176, v176
	v_rcp_f32_e32 v177, v177
	v_cvt_pk_bf16_f32 v118, v174, v175
	v_cvt_pk_bf16_f32 v119, v176, v177
	global_store_short v210, v118, s[30:31] offset:32
	global_store_short_d16_hi v211, v118, s[30:31] offset:32
	global_store_short v212, v119, s[30:31] offset:32
	global_store_short_d16_hi v213, v119, s[30:31] offset:32
	v_pk_mul_f32 v[122:123], v[122:123], v[178:179]
	v_pk_mul_f32 v[124:125], v[124:125], v[180:181]
	v_pk_mul_f32 v[174:175], v[214:215], v[122:123]
	v_pk_mul_f32 v[176:177], v[214:215], v[124:125]
	v_exp_f32_e32 v174, v174
	v_exp_f32_e32 v175, v175
	v_exp_f32_e32 v176, v176
	v_exp_f32_e32 v177, v177
	v_pk_add_f32 v[174:175], v[216:217], v[174:175]
	v_pk_add_f32 v[176:177], v[216:217], v[176:177]
	v_rcp_f32_e32 v174, v174
	v_rcp_f32_e32 v175, v175
	v_rcp_f32_e32 v176, v176
	v_rcp_f32_e32 v177, v177
	v_cvt_pk_bf16_f32 v122, v174, v175
	v_cvt_pk_bf16_f32 v123, v176, v177
	global_store_short v210, v122, s[30:31] offset:256
	global_store_short_d16_hi v211, v122, s[30:31] offset:256
	global_store_short v212, v123, s[30:31] offset:256
	global_store_short_d16_hi v213, v123, s[30:31] offset:256
	v_pk_mul_f32 v[126:127], v[126:127], v[178:179]
	v_pk_mul_f32 v[128:129], v[128:129], v[180:181]
	v_pk_mul_f32 v[174:175], v[214:215], v[126:127]
	v_pk_mul_f32 v[176:177], v[214:215], v[128:129]
	v_exp_f32_e32 v174, v174
	v_exp_f32_e32 v175, v175
	v_exp_f32_e32 v176, v176
	v_exp_f32_e32 v177, v177
	v_pk_add_f32 v[174:175], v[216:217], v[174:175]
	v_pk_add_f32 v[176:177], v[216:217], v[176:177]
	v_rcp_f32_e32 v174, v174
	v_rcp_f32_e32 v175, v175
	v_rcp_f32_e32 v176, v176
	v_rcp_f32_e32 v177, v177
	v_cvt_pk_bf16_f32 v126, v174, v175
	v_cvt_pk_bf16_f32 v127, v176, v177
	global_store_short v210, v126, s[30:31] offset:288
	global_store_short_d16_hi v211, v126, s[30:31] offset:288
	global_store_short v212, v127, s[30:31] offset:288
	global_store_short_d16_hi v213, v127, s[30:31] offset:288
	s_add_u32 s30, s30, s4
	s_addc_u32 s31, s31, 0
	v_pk_mul_f32 v[102:103], v[102:103], v[182:183]
	v_pk_mul_f32 v[104:105], v[104:105], v[184:185]
	v_pk_mul_f32 v[174:175], v[214:215], v[102:103]
	v_pk_mul_f32 v[176:177], v[214:215], v[104:105]
	v_exp_f32_e32 v174, v174
	v_exp_f32_e32 v175, v175
	v_exp_f32_e32 v176, v176
	v_exp_f32_e32 v177, v177
	v_pk_add_f32 v[174:175], v[216:217], v[174:175]
	v_pk_add_f32 v[176:177], v[216:217], v[176:177]
	v_rcp_f32_e32 v174, v174
	v_rcp_f32_e32 v175, v175
	v_rcp_f32_e32 v176, v176
	v_rcp_f32_e32 v177, v177
	v_cvt_pk_bf16_f32 v102, v174, v175
; __device__ __forceinline__ float sigmoidf_(float v) { return __builtin_amdgcn_rcpf(1.f + __builtin_amdgcn_exp2f(-LOG2E * v)); }
; __device__ __forceinline__ void phase_inproj() {
;     ...
;       if (sg) { INPROJ_STORE(sigmoidf_(v)) } else { INPROJ_STORE(v) }
	v_cvt_pk_bf16_f32 v103, v176, v177
	global_store_short v210, v102, s[30:31]
	global_store_short_d16_hi v211, v102, s[30:31]
	global_store_short v212, v103, s[30:31]
	global_store_short_d16_hi v213, v103, s[30:31]
	v_pk_mul_f32 v[98:99], v[98:99], v[182:183]
	v_pk_mul_f32 v[100:101], v[100:101], v[184:185]
	v_pk_mul_f32 v[174:175], v[214:215], v[98:99]
	v_pk_mul_f32 v[176:177], v[214:215], v[100:101]
	v_exp_f32_e32 v174, v174
	v_exp_f32_e32 v175, v175
	v_exp_f32_e32 v176, v176
	v_exp_f32_e32 v177, v177
	v_pk_add_f32 v[174:175], v[216:217], v[174:175]
	v_pk_add_f32 v[176:177], v[216:217], v[176:177]
	v_rcp_f32_e32 v174, v174
	v_rcp_f32_e32 v175, v175
	v_rcp_f32_e32 v176, v176
	v_rcp_f32_e32 v177, v177
	v_cvt_pk_bf16_f32 v98, v174, v175
	v_cvt_pk_bf16_f32 v99, v176, v177
	global_store_short v210, v98, s[30:31] offset:32
	global_store_short_d16_hi v211, v98, s[30:31] offset:32
	global_store_short v212, v99, s[30:31] offset:32
	global_store_short_d16_hi v213, v99, s[30:31] offset:32
	v_pk_mul_f32 v[106:107], v[106:107], v[182:183]
	v_pk_mul_f32 v[108:109], v[108:109], v[184:185]
	v_pk_mul_f32 v[174:175], v[214:215], v[106:107]
	v_pk_mul_f32 v[176:177], v[214:215], v[108:109]
	v_exp_f32_e32 v174, v174
	v_exp_f32_e32 v175, v175
	v_exp_f32_e32 v176, v176
	v_exp_f32_e32 v177, v177
	v_pk_add_f32 v[174:175], v[216:217], v[174:175]
	v_pk_add_f32 v[176:177], v[216:217], v[176:177]
	v_rcp_f32_e32 v174, v174
	v_rcp_f32_e32 v175, v175
	v_rcp_f32_e32 v176, v176
	v_rcp_f32_e32 v177, v177
	v_cvt_pk_bf16_f32 v106, v174, v175
	v_cvt_pk_bf16_f32 v107, v176, v177
	global_store_short v210, v106, s[30:31] offset:256
	global_store_short_d16_hi v211, v106, s[30:31] offset:256
	global_store_short v212, v107, s[30:31] offset:256
	global_store_short_d16_hi v213, v107, s[30:31] offset:256
	v_pk_mul_f32 v[110:111], v[110:111], v[182:183]
	v_pk_mul_f32 v[112:113], v[112:113], v[184:185]
	v_pk_mul_f32 v[174:175], v[214:215], v[110:111]
	v_pk_mul_f32 v[176:177], v[214:215], v[112:113]
	v_exp_f32_e32 v174, v174
	v_exp_f32_e32 v175, v175
	v_exp_f32_e32 v176, v176
	v_exp_f32_e32 v177, v177
	v_pk_add_f32 v[174:175], v[216:217], v[174:175]
	v_pk_add_f32 v[176:177], v[216:217], v[176:177]
	v_rcp_f32_e32 v174, v174
	v_rcp_f32_e32 v175, v175
	v_rcp_f32_e32 v176, v176
	v_rcp_f32_e32 v177, v177
	v_cvt_pk_bf16_f32 v110, v174, v175
	v_cvt_pk_bf16_f32 v111, v176, v177
	global_store_short v210, v110, s[30:31] offset:288
	global_store_short_d16_hi v211, v110, s[30:31] offset:288
	global_store_short v212, v111, s[30:31] offset:288
	global_store_short_d16_hi v213, v111, s[30:31] offset:288
	s_add_u32 s30, s30, s4
	s_addc_u32 s31, s31, 0
	v_pk_mul_f32 v[82:83], v[82:83], v[186:187]
	v_pk_mul_f32 v[84:85], v[84:85], v[188:189]
	v_pk_mul_f32 v[174:175], v[214:215], v[82:83]
	v_pk_mul_f32 v[176:177], v[214:215], v[84:85]
	v_exp_f32_e32 v174, v174
	v_exp_f32_e32 v175, v175
	v_exp_f32_e32 v176, v176
	v_exp_f32_e32 v177, v177
	v_pk_add_f32 v[174:175], v[216:217], v[174:175]
	v_pk_add_f32 v[176:177], v[216:217], v[176:177]
	v_rcp_f32_e32 v174, v174
	v_rcp_f32_e32 v175, v175
	v_rcp_f32_e32 v176, v176
	v_rcp_f32_e32 v177, v177
	v_cvt_pk_bf16_f32 v82, v174, v175
	v_cvt_pk_bf16_f32 v83, v176, v177
	global_store_short v210, v82, s[30:31]
	global_store_short_d16_hi v211, v82, s[30:31]
	global_store_short v212, v83, s[30:31]
	global_store_short_d16_hi v213, v83, s[30:31]
	v_pk_mul_f32 v[86:87], v[86:87], v[186:187]
	v_pk_mul_f32 v[88:89], v[88:89], v[188:189]
	v_pk_mul_f32 v[174:175], v[214:215], v[86:87]
	v_pk_mul_f32 v[176:177], v[214:215], v[88:89]
	v_exp_f32_e32 v174, v174
	v_exp_f32_e32 v175, v175
	v_exp_f32_e32 v176, v176
	v_exp_f32_e32 v177, v177
	v_pk_add_f32 v[174:175], v[216:217], v[174:175]
	v_pk_add_f32 v[176:177], v[216:217], v[176:177]
	v_rcp_f32_e32 v174, v174
	v_rcp_f32_e32 v175, v175
	v_rcp_f32_e32 v176, v176
	v_rcp_f32_e32 v177, v177
	v_cvt_pk_bf16_f32 v86, v174, v175
	v_cvt_pk_bf16_f32 v87, v176, v177
	global_store_short v210, v86, s[30:31] offset:32
	global_store_short_d16_hi v211, v86, s[30:31] offset:32
	global_store_short v212, v87, s[30:31] offset:32
	global_store_short_d16_hi v213, v87, s[30:31] offset:32
	v_pk_mul_f32 v[90:91], v[90:91], v[186:187]
	v_pk_mul_f32 v[92:93], v[92:93], v[188:189]
	v_pk_mul_f32 v[174:175], v[214:215], v[90:91]
	v_pk_mul_f32 v[176:177], v[214:215], v[92:93]
	v_exp_f32_e32 v174, v174
	v_exp_f32_e32 v175, v175
	v_exp_f32_e32 v176, v176
	v_exp_f32_e32 v177, v177
	v_pk_add_f32 v[174:175], v[216:217], v[174:175]
	v_pk_add_f32 v[176:177], v[216:217], v[176:177]
	v_rcp_f32_e32 v174, v174
	v_rcp_f32_e32 v175, v175
	v_rcp_f32_e32 v176, v176
	v_rcp_f32_e32 v177, v177
	v_cvt_pk_bf16_f32 v90, v174, v175
	v_cvt_pk_bf16_f32 v91, v176, v177
	global_store_short v210, v90, s[30:31] offset:256
	global_store_short_d16_hi v211, v90, s[30:31] offset:256
	global_store_short v212, v91, s[30:31] offset:256
	global_store_short_d16_hi v213, v91, s[30:31] offset:256
	v_pk_mul_f32 v[94:95], v[94:95], v[186:187]
	v_pk_mul_f32 v[96:97], v[96:97], v[188:189]
	v_pk_mul_f32 v[174:175], v[214:215], v[94:95]
	v_pk_mul_f32 v[176:177], v[214:215], v[96:97]
	v_exp_f32_e32 v174, v174
	v_exp_f32_e32 v175, v175
	v_exp_f32_e32 v176, v176
	v_exp_f32_e32 v177, v177
	v_pk_add_f32 v[174:175], v[216:217], v[174:175]
	v_pk_add_f32 v[176:177], v[216:217], v[176:177]
	v_rcp_f32_e32 v174, v174
	v_rcp_f32_e32 v175, v175
	v_rcp_f32_e32 v176, v176
	v_rcp_f32_e32 v177, v177
	v_cvt_pk_bf16_f32 v94, v174, v175
	v_cvt_pk_bf16_f32 v95, v176, v177
	global_store_short v210, v94, s[30:31] offset:288
	global_store_short_d16_hi v211, v94, s[30:31] offset:288
	global_store_short v212, v95, s[30:31] offset:288
; __device__ __forceinline__ float sigmoidf_(float v) { return __builtin_amdgcn_rcpf(1.f + __builtin_amdgcn_exp2f(-LOG2E * v)); }
; __device__ __forceinline__ void phase_inproj() {
;     ...
;       if (sg) { INPROJ_STORE(sigmoidf_(v)) } else { INPROJ_STORE(v) }
	global_store_short_d16_hi v213, v95, s[30:31] offset:288
	s_add_u32 s30, s30, s4
	s_addc_u32 s31, s31, 0
	v_pk_mul_f32 v[70:71], v[70:71], v[190:191]
	v_pk_mul_f32 v[72:73], v[72:73], v[192:193]
	v_pk_mul_f32 v[174:175], v[214:215], v[70:71]
	v_pk_mul_f32 v[176:177], v[214:215], v[72:73]
	v_exp_f32_e32 v174, v174
	v_exp_f32_e32 v175, v175
	v_exp_f32_e32 v176, v176
	v_exp_f32_e32 v177, v177
	v_pk_add_f32 v[174:175], v[216:217], v[174:175]
	v_pk_add_f32 v[176:177], v[216:217], v[176:177]
	v_rcp_f32_e32 v174, v174
	v_rcp_f32_e32 v175, v175
	v_rcp_f32_e32 v176, v176
	v_rcp_f32_e32 v177, v177
	v_cvt_pk_bf16_f32 v70, v174, v175
	v_cvt_pk_bf16_f32 v71, v176, v177
	global_store_short v210, v70, s[30:31]
	global_store_short_d16_hi v211, v70, s[30:31]
	global_store_short v212, v71, s[30:31]
	global_store_short_d16_hi v213, v71, s[30:31]
	v_pk_mul_f32 v[66:67], v[66:67], v[190:191]
	v_pk_mul_f32 v[68:69], v[68:69], v[192:193]
	v_pk_mul_f32 v[174:175], v[214:215], v[66:67]
	v_pk_mul_f32 v[176:177], v[214:215], v[68:69]
	v_exp_f32_e32 v174, v174
	v_exp_f32_e32 v175, v175
	v_exp_f32_e32 v176, v176
	v_exp_f32_e32 v177, v177
	v_pk_add_f32 v[174:175], v[216:217], v[174:175]
	v_pk_add_f32 v[176:177], v[216:217], v[176:177]
	v_rcp_f32_e32 v174, v174
	v_rcp_f32_e32 v175, v175
	v_rcp_f32_e32 v176, v176
	v_rcp_f32_e32 v177, v177
	v_cvt_pk_bf16_f32 v66, v174, v175
	v_cvt_pk_bf16_f32 v67, v176, v177
	global_store_short v210, v66, s[30:31] offset:32
	global_store_short_d16_hi v211, v66, s[30:31] offset:32
	global_store_short v212, v67, s[30:31] offset:32
	global_store_short_d16_hi v213, v67, s[30:31] offset:32
	v_pk_mul_f32 v[74:75], v[74:75], v[190:191]
	v_pk_mul_f32 v[76:77], v[76:77], v[192:193]
	v_pk_mul_f32 v[174:175], v[214:215], v[74:75]
	v_pk_mul_f32 v[176:177], v[214:215], v[76:77]
	v_exp_f32_e32 v174, v174
	v_exp_f32_e32 v175, v175
	v_exp_f32_e32 v176, v176
	v_exp_f32_e32 v177, v177
	v_pk_add_f32 v[174:175], v[216:217], v[174:175]
	v_pk_add_f32 v[176:177], v[216:217], v[176:177]
	v_rcp_f32_e32 v174, v174
	v_rcp_f32_e32 v175, v175
	v_rcp_f32_e32 v176, v176
	v_rcp_f32_e32 v177, v177
	v_cvt_pk_bf16_f32 v74, v174, v175
	v_cvt_pk_bf16_f32 v75, v176, v177
	global_store_short v210, v74, s[30:31] offset:256
	global_store_short_d16_hi v211, v74, s[30:31] offset:256
	global_store_short v212, v75, s[30:31] offset:256
	global_store_short_d16_hi v213, v75, s[30:31] offset:256
	v_pk_mul_f32 v[78:79], v[78:79], v[190:191]
	v_pk_mul_f32 v[80:81], v[80:81], v[192:193]
	v_pk_mul_f32 v[174:175], v[214:215], v[78:79]
	v_pk_mul_f32 v[176:177], v[214:215], v[80:81]
	v_exp_f32_e32 v174, v174
	v_exp_f32_e32 v175, v175
	v_exp_f32_e32 v176, v176
	v_exp_f32_e32 v177, v177
	v_pk_add_f32 v[174:175], v[216:217], v[174:175]
	v_pk_add_f32 v[176:177], v[216:217], v[176:177]
	v_rcp_f32_e32 v174, v174
	v_rcp_f32_e32 v175, v175
	v_rcp_f32_e32 v176, v176
	v_rcp_f32_e32 v177, v177
	v_cvt_pk_bf16_f32 v78, v174, v175
	v_cvt_pk_bf16_f32 v79, v176, v177
	global_store_short v210, v78, s[30:31] offset:288
	global_store_short_d16_hi v211, v78, s[30:31] offset:288
	global_store_short v212, v79, s[30:31] offset:288
	global_store_short_d16_hi v213, v79, s[30:31] offset:288
	s_add_u32 s30, s30, s5
	s_addc_u32 s31, s31, 0
	v_pk_mul_f32 v[50:51], v[50:51], v[194:195]
	v_pk_mul_f32 v[52:53], v[52:53], v[196:197]
	v_pk_mul_f32 v[174:175], v[214:215], v[50:51]
	v_pk_mul_f32 v[176:177], v[214:215], v[52:53]
	v_exp_f32_e32 v174, v174
	v_exp_f32_e32 v175, v175
	v_exp_f32_e32 v176, v176
	v_exp_f32_e32 v177, v177
	v_pk_add_f32 v[174:175], v[216:217], v[174:175]
	v_pk_add_f32 v[176:177], v[216:217], v[176:177]
	v_rcp_f32_e32 v174, v174
	v_rcp_f32_e32 v175, v175
	v_rcp_f32_e32 v176, v176
	v_rcp_f32_e32 v177, v177
	v_cvt_pk_bf16_f32 v50, v174, v175
	v_cvt_pk_bf16_f32 v51, v176, v177
	global_store_short v210, v50, s[30:31]
	global_store_short_d16_hi v211, v50, s[30:31]
	global_store_short v212, v51, s[30:31]
	global_store_short_d16_hi v213, v51, s[30:31]
	v_pk_mul_f32 v[54:55], v[54:55], v[194:195]
	v_pk_mul_f32 v[56:57], v[56:57], v[196:197]
	v_pk_mul_f32 v[174:175], v[214:215], v[54:55]
	v_pk_mul_f32 v[176:177], v[214:215], v[56:57]
	v_exp_f32_e32 v174, v174
	v_exp_f32_e32 v175, v175
	v_exp_f32_e32 v176, v176
	v_exp_f32_e32 v177, v177
	v_pk_add_f32 v[174:175], v[216:217], v[174:175]
	v_pk_add_f32 v[176:177], v[216:217], v[176:177]
	v_rcp_f32_e32 v174, v174
	v_rcp_f32_e32 v175, v175
	v_rcp_f32_e32 v176, v176
	v_rcp_f32_e32 v177, v177
	v_cvt_pk_bf16_f32 v54, v174, v175
	v_cvt_pk_bf16_f32 v55, v176, v177
	global_store_short v210, v54, s[30:31] offset:32
	global_store_short_d16_hi v211, v54, s[30:31] offset:32
	global_store_short v212, v55, s[30:31] offset:32
	global_store_short_d16_hi v213, v55, s[30:31] offset:32
	v_pk_mul_f32 v[58:59], v[58:59], v[194:195]
	v_pk_mul_f32 v[60:61], v[60:61], v[196:197]
	v_pk_mul_f32 v[174:175], v[214:215], v[58:59]
	v_pk_mul_f32 v[176:177], v[214:215], v[60:61]
	v_exp_f32_e32 v174, v174
	v_exp_f32_e32 v175, v175
	v_exp_f32_e32 v176, v176
	v_exp_f32_e32 v177, v177
	v_pk_add_f32 v[174:175], v[216:217], v[174:175]
	v_pk_add_f32 v[176:177], v[216:217], v[176:177]
	v_rcp_f32_e32 v174, v174
	v_rcp_f32_e32 v175, v175
	v_rcp_f32_e32 v176, v176
	v_rcp_f32_e32 v177, v177
	v_cvt_pk_bf16_f32 v58, v174, v175
	v_cvt_pk_bf16_f32 v59, v176, v177
	global_store_short v210, v58, s[30:31] offset:256
	global_store_short_d16_hi v211, v58, s[30:31] offset:256
	global_store_short v212, v59, s[30:31] offset:256
	global_store_short_d16_hi v213, v59, s[30:31] offset:256
	v_pk_mul_f32 v[62:63], v[62:63], v[194:195]
	v_pk_mul_f32 v[64:65], v[64:65], v[196:197]
	v_pk_mul_f32 v[174:175], v[214:215], v[62:63]
; __device__ __forceinline__ float sigmoidf_(float v) { return __builtin_amdgcn_rcpf(1.f + __builtin_amdgcn_exp2f(-LOG2E * v)); }
; __device__ __forceinline__ void phase_inproj() {
;     ...
;       if (sg) { INPROJ_STORE(sigmoidf_(v)) } else { INPROJ_STORE(v) }
	v_pk_mul_f32 v[176:177], v[214:215], v[64:65]
	v_exp_f32_e32 v174, v174
	v_exp_f32_e32 v175, v175
	v_exp_f32_e32 v176, v176
	v_exp_f32_e32 v177, v177
	v_pk_add_f32 v[174:175], v[216:217], v[174:175]
	v_pk_add_f32 v[176:177], v[216:217], v[176:177]
	v_rcp_f32_e32 v174, v174
	v_rcp_f32_e32 v175, v175
	v_rcp_f32_e32 v176, v176
	v_rcp_f32_e32 v177, v177
	v_cvt_pk_bf16_f32 v62, v174, v175
	v_cvt_pk_bf16_f32 v63, v176, v177
	global_store_short v210, v62, s[30:31] offset:288
	global_store_short_d16_hi v211, v62, s[30:31] offset:288
	global_store_short v212, v63, s[30:31] offset:288
	global_store_short_d16_hi v213, v63, s[30:31] offset:288
	s_add_u32 s30, s30, s4
	s_addc_u32 s31, s31, 0
	v_pk_mul_f32 v[38:39], v[38:39], v[198:199]
	v_pk_mul_f32 v[40:41], v[40:41], v[200:201]
	v_pk_mul_f32 v[174:175], v[214:215], v[38:39]
	v_pk_mul_f32 v[176:177], v[214:215], v[40:41]
	v_exp_f32_e32 v174, v174
	v_exp_f32_e32 v175, v175
	v_exp_f32_e32 v176, v176
	v_exp_f32_e32 v177, v177
	v_pk_add_f32 v[174:175], v[216:217], v[174:175]
	v_pk_add_f32 v[176:177], v[216:217], v[176:177]
	v_rcp_f32_e32 v174, v174
	v_rcp_f32_e32 v175, v175
	v_rcp_f32_e32 v176, v176
	v_rcp_f32_e32 v177, v177
	v_cvt_pk_bf16_f32 v38, v174, v175
	v_cvt_pk_bf16_f32 v39, v176, v177
	global_store_short v210, v38, s[30:31]
	global_store_short_d16_hi v211, v38, s[30:31]
	global_store_short v212, v39, s[30:31]
	global_store_short_d16_hi v213, v39, s[30:31]
	v_pk_mul_f32 v[34:35], v[34:35], v[198:199]
	v_pk_mul_f32 v[36:37], v[36:37], v[200:201]
	v_pk_mul_f32 v[174:175], v[214:215], v[34:35]
	v_pk_mul_f32 v[176:177], v[214:215], v[36:37]
	v_exp_f32_e32 v174, v174
	v_exp_f32_e32 v175, v175
	v_exp_f32_e32 v176, v176
	v_exp_f32_e32 v177, v177
	v_pk_add_f32 v[174:175], v[216:217], v[174:175]
	v_pk_add_f32 v[176:177], v[216:217], v[176:177]
	v_rcp_f32_e32 v174, v174
	v_rcp_f32_e32 v175, v175
	v_rcp_f32_e32 v176, v176
	v_rcp_f32_e32 v177, v177
	v_cvt_pk_bf16_f32 v34, v174, v175
	v_cvt_pk_bf16_f32 v35, v176, v177
	global_store_short v210, v34, s[30:31] offset:32
	global_store_short_d16_hi v211, v34, s[30:31] offset:32
	global_store_short v212, v35, s[30:31] offset:32
	global_store_short_d16_hi v213, v35, s[30:31] offset:32
	v_pk_mul_f32 v[42:43], v[42:43], v[198:199]
	v_pk_mul_f32 v[44:45], v[44:45], v[200:201]
	v_pk_mul_f32 v[174:175], v[214:215], v[42:43]
	v_pk_mul_f32 v[176:177], v[214:215], v[44:45]
	v_exp_f32_e32 v174, v174
	v_exp_f32_e32 v175, v175
	v_exp_f32_e32 v176, v176
	v_exp_f32_e32 v177, v177
	v_pk_add_f32 v[174:175], v[216:217], v[174:175]
	v_pk_add_f32 v[176:177], v[216:217], v[176:177]
	v_rcp_f32_e32 v174, v174
	v_rcp_f32_e32 v175, v175
	v_rcp_f32_e32 v176, v176
	v_rcp_f32_e32 v177, v177
	v_cvt_pk_bf16_f32 v42, v174, v175
	v_cvt_pk_bf16_f32 v43, v176, v177
	global_store_short v210, v42, s[30:31] offset:256
	global_store_short_d16_hi v211, v42, s[30:31] offset:256
	global_store_short v212, v43, s[30:31] offset:256
	global_store_short_d16_hi v213, v43, s[30:31] offset:256
	v_pk_mul_f32 v[46:47], v[46:47], v[198:199]
	v_pk_mul_f32 v[48:49], v[48:49], v[200:201]
	v_pk_mul_f32 v[174:175], v[214:215], v[46:47]
	v_pk_mul_f32 v[176:177], v[214:215], v[48:49]
	v_exp_f32_e32 v174, v174
	v_exp_f32_e32 v175, v175
	v_exp_f32_e32 v176, v176
	v_exp_f32_e32 v177, v177
	v_pk_add_f32 v[174:175], v[216:217], v[174:175]
	v_pk_add_f32 v[176:177], v[216:217], v[176:177]
	v_rcp_f32_e32 v174, v174
	v_rcp_f32_e32 v175, v175
	v_rcp_f32_e32 v176, v176
	v_rcp_f32_e32 v177, v177
	v_cvt_pk_bf16_f32 v46, v174, v175
	v_cvt_pk_bf16_f32 v47, v176, v177
	global_store_short v210, v46, s[30:31] offset:288
	global_store_short_d16_hi v211, v46, s[30:31] offset:288
	global_store_short v212, v47, s[30:31] offset:288
	global_store_short_d16_hi v213, v47, s[30:31] offset:288
	s_add_u32 s30, s30, s4
	s_addc_u32 s31, s31, 0
	v_pk_mul_f32 v[18:19], v[18:19], v[202:203]
	v_pk_mul_f32 v[20:21], v[20:21], v[204:205]
	v_pk_mul_f32 v[174:175], v[214:215], v[18:19]
	v_pk_mul_f32 v[176:177], v[214:215], v[20:21]
	v_exp_f32_e32 v174, v174
	v_exp_f32_e32 v175, v175
	v_exp_f32_e32 v176, v176
	v_exp_f32_e32 v177, v177
	v_pk_add_f32 v[174:175], v[216:217], v[174:175]
	v_pk_add_f32 v[176:177], v[216:217], v[176:177]
	v_rcp_f32_e32 v174, v174
	v_rcp_f32_e32 v175, v175
	v_rcp_f32_e32 v176, v176
	v_rcp_f32_e32 v177, v177
	v_cvt_pk_bf16_f32 v18, v174, v175
	v_cvt_pk_bf16_f32 v19, v176, v177
	global_store_short v210, v18, s[30:31]
	global_store_short_d16_hi v211, v18, s[30:31]
	global_store_short v212, v19, s[30:31]
	global_store_short_d16_hi v213, v19, s[30:31]
	v_pk_mul_f32 v[22:23], v[22:23], v[202:203]
	v_pk_mul_f32 v[24:25], v[24:25], v[204:205]
	v_pk_mul_f32 v[174:175], v[214:215], v[22:23]
	v_pk_mul_f32 v[176:177], v[214:215], v[24:25]
	v_exp_f32_e32 v174, v174
	v_exp_f32_e32 v175, v175
	v_exp_f32_e32 v176, v176
	v_exp_f32_e32 v177, v177
	v_pk_add_f32 v[174:175], v[216:217], v[174:175]
	v_pk_add_f32 v[176:177], v[216:217], v[176:177]
	v_rcp_f32_e32 v174, v174
	v_rcp_f32_e32 v175, v175
; __device__ __forceinline__ float sigmoidf_(float v) { return __builtin_amdgcn_rcpf(1.f + __builtin_amdgcn_exp2f(-LOG2E * v)); }
; __device__ __forceinline__ void phase_inproj() {
;     ...
;       if (sg) { INPROJ_STORE(sigmoidf_(v)) } else { INPROJ_STORE(v) }
	v_rcp_f32_e32 v176, v176
	v_rcp_f32_e32 v177, v177
	v_cvt_pk_bf16_f32 v22, v174, v175
	v_cvt_pk_bf16_f32 v23, v176, v177
	global_store_short v210, v22, s[30:31] offset:32
	global_store_short_d16_hi v211, v22, s[30:31] offset:32
	global_store_short v212, v23, s[30:31] offset:32
	global_store_short_d16_hi v213, v23, s[30:31] offset:32
	v_pk_mul_f32 v[26:27], v[26:27], v[202:203]
	v_pk_mul_f32 v[28:29], v[28:29], v[204:205]
	v_pk_mul_f32 v[174:175], v[214:215], v[26:27]
	v_pk_mul_f32 v[176:177], v[214:215], v[28:29]
	v_exp_f32_e32 v174, v174
	v_exp_f32_e32 v175, v175
	v_exp_f32_e32 v176, v176
	v_exp_f32_e32 v177, v177
	v_pk_add_f32 v[174:175], v[216:217], v[174:175]
	v_pk_add_f32 v[176:177], v[216:217], v[176:177]
	v_rcp_f32_e32 v174, v174
	v_rcp_f32_e32 v175, v175
	v_rcp_f32_e32 v176, v176
	v_rcp_f32_e32 v177, v177
	v_cvt_pk_bf16_f32 v26, v174, v175
	v_cvt_pk_bf16_f32 v27, v176, v177
	global_store_short v210, v26, s[30:31] offset:256
	global_store_short_d16_hi v211, v26, s[30:31] offset:256
	global_store_short v212, v27, s[30:31] offset:256
	global_store_short_d16_hi v213, v27, s[30:31] offset:256
	v_pk_mul_f32 v[30:31], v[30:31], v[202:203]
	v_pk_mul_f32 v[32:33], v[32:33], v[204:205]
	v_pk_mul_f32 v[174:175], v[214:215], v[30:31]
	v_pk_mul_f32 v[176:177], v[214:215], v[32:33]
	v_exp_f32_e32 v174, v174
	v_exp_f32_e32 v175, v175
	v_exp_f32_e32 v176, v176
	v_exp_f32_e32 v177, v177
	v_pk_add_f32 v[174:175], v[216:217], v[174:175]
	v_pk_add_f32 v[176:177], v[216:217], v[176:177]
	v_rcp_f32_e32 v174, v174
	v_rcp_f32_e32 v175, v175
	v_rcp_f32_e32 v176, v176
	v_rcp_f32_e32 v177, v177
	v_cvt_pk_bf16_f32 v30, v174, v175
	v_cvt_pk_bf16_f32 v31, v176, v177
	global_store_short v210, v30, s[30:31] offset:288
	global_store_short_d16_hi v211, v30, s[30:31] offset:288
	global_store_short v212, v31, s[30:31] offset:288
	global_store_short_d16_hi v213, v31, s[30:31] offset:288
	s_add_u32 s30, s30, s4
	s_addc_u32 s31, s31, 0
	v_pk_mul_f32 v[6:7], v[6:7], v[206:207]
	v_pk_mul_f32 v[8:9], v[8:9], v[208:209]
	v_pk_mul_f32 v[174:175], v[214:215], v[6:7]
	v_pk_mul_f32 v[176:177], v[214:215], v[8:9]
	v_exp_f32_e32 v174, v174
	v_exp_f32_e32 v175, v175
	v_exp_f32_e32 v176, v176
	v_exp_f32_e32 v177, v177
	v_pk_add_f32 v[174:175], v[216:217], v[174:175]
	v_pk_add_f32 v[176:177], v[216:217], v[176:177]
	v_rcp_f32_e32 v174, v174
	v_rcp_f32_e32 v175, v175
	v_rcp_f32_e32 v176, v176
	v_rcp_f32_e32 v177, v177
	v_cvt_pk_bf16_f32 v6, v174, v175
	v_cvt_pk_bf16_f32 v7, v176, v177
	global_store_short v210, v6, s[30:31]
	global_store_short_d16_hi v211, v6, s[30:31]
	global_store_short v212, v7, s[30:31]
	global_store_short_d16_hi v213, v7, s[30:31]
	v_pk_mul_f32 v[2:3], v[2:3], v[206:207]
	v_pk_mul_f32 v[4:5], v[4:5], v[208:209]
	v_pk_mul_f32 v[174:175], v[214:215], v[2:3]
	v_pk_mul_f32 v[176:177], v[214:215], v[4:5]
	v_exp_f32_e32 v174, v174
	v_exp_f32_e32 v175, v175
	v_exp_f32_e32 v176, v176
	v_exp_f32_e32 v177, v177
	v_pk_add_f32 v[174:175], v[216:217], v[174:175]
	v_pk_add_f32 v[176:177], v[216:217], v[176:177]
	v_rcp_f32_e32 v174, v174
	v_rcp_f32_e32 v175, v175
	v_rcp_f32_e32 v176, v176
	v_rcp_f32_e32 v177, v177
	v_cvt_pk_bf16_f32 v2, v174, v175
	v_cvt_pk_bf16_f32 v3, v176, v177
	global_store_short v210, v2, s[30:31] offset:32
	global_store_short_d16_hi v211, v2, s[30:31] offset:32
	global_store_short v212, v3, s[30:31] offset:32
	global_store_short_d16_hi v213, v3, s[30:31] offset:32
	v_pk_mul_f32 v[10:11], v[10:11], v[206:207]
	v_pk_mul_f32 v[12:13], v[12:13], v[208:209]
	v_pk_mul_f32 v[174:175], v[214:215], v[10:11]
	v_pk_mul_f32 v[176:177], v[214:215], v[12:13]
	v_exp_f32_e32 v174, v174
	v_exp_f32_e32 v175, v175
	v_exp_f32_e32 v176, v176
	v_exp_f32_e32 v177, v177
	v_pk_add_f32 v[174:175], v[216:217], v[174:175]
	v_pk_add_f32 v[176:177], v[216:217], v[176:177]
	v_rcp_f32_e32 v174, v174
	v_rcp_f32_e32 v175, v175
	v_rcp_f32_e32 v176, v176
	v_rcp_f32_e32 v177, v177
	v_cvt_pk_bf16_f32 v10, v174, v175
	v_cvt_pk_bf16_f32 v11, v176, v177
	global_store_short v210, v10, s[30:31] offset:256
	global_store_short_d16_hi v211, v10, s[30:31] offset:256
	global_store_short v212, v11, s[30:31] offset:256
	global_store_short_d16_hi v213, v11, s[30:31] offset:256
	v_pk_mul_f32 v[14:15], v[14:15], v[206:207]
	v_pk_mul_f32 v[16:17], v[16:17], v[208:209]
	v_pk_mul_f32 v[174:175], v[214:215], v[14:15]
	v_pk_mul_f32 v[176:177], v[214:215], v[16:17]
	v_exp_f32_e32 v174, v174
	v_exp_f32_e32 v175, v175
	v_exp_f32_e32 v176, v176
	v_exp_f32_e32 v177, v177
	v_pk_add_f32 v[174:175], v[216:217], v[174:175]
	v_pk_add_f32 v[176:177], v[216:217], v[176:177]
	v_rcp_f32_e32 v174, v174
	v_rcp_f32_e32 v175, v175
	v_rcp_f32_e32 v176, v176
	v_rcp_f32_e32 v177, v177
	v_cvt_pk_bf16_f32 v14, v174, v175
	v_cvt_pk_bf16_f32 v15, v176, v177
	global_store_short v210, v14, s[30:31] offset:288
	global_store_short_d16_hi v211, v14, s[30:31] offset:288
	global_store_short v212, v15, s[30:31] offset:288
	global_store_short_d16_hi v213, v15, s[30:31] offset:288
